# attn loop: S acc relocated (no v_mov_b64 copies), K frags prefetched, PV V-frag ring 6 ahead, max tree reordered
# speedup vs baseline: 1.0092x; 1.0092x over previous
.LBB0_666:
	s_waitcnt vmcnt(0) lgkmcnt(0)
	s_barrier
	s_and_b32 s36, s24, 1
	s_add_i32 s75, s24, 1
	v_lshl_add_u32 v226, s36, 14, v233
	ds_read_b128 v[82:85], v226
	ds_read_b128 v[86:89], v226 offset:512
	ds_read_b128 v[90:93], v226 offset:2048
	ds_read_b128 v[94:97], v226 offset:2560
	ds_read_b128 v[98:101], v226 offset:4096
	ds_read_b128 v[102:105], v226 offset:4608
	ds_read_b128 v[106:109], v226 offset:6144
	ds_read_b128 v[110:113], v226 offset:6656
	s_cmp_ge_u32 s75, s72
	s_cbranch_scc1 .LBB0_668
	s_xor_b32 s6, s36, 1
	v_lshl_add_u64 v[140:141], v[238:239], 0, s[56:57]
	s_mov_b64 s[58:59], 0x40000
	s_lshl_b32 s7, s6, 14
	v_lshl_add_u64 v[142:143], v[140:141], 0, s[58:59]
	s_add_i32 s7, s7, s69
	s_lshl_b32 s6, s6, 15
	s_mov_b32 s25, m0
	s_mov_b32 m0, s7
	s_nop 0
	global_load_lds_dwordx4 v[142:143], off
	s_mov_b32 m0, s25
	v_lshl_add_u64 v[142:143], v[240:241], 0, s[56:57]
	s_mov_b64 s[58:59], 0x20040000
	s_add_i32 s6, s6, s70
	v_lshl_add_u64 v[144:145], v[142:143], 0, s[58:59]
	s_mov_b32 s25, m0
	s_mov_b32 m0, s6
	s_nop 0
	global_load_lds_dwordx4 v[144:145], off
	s_mov_b32 m0, s25
	s_mov_b64 s[58:59], 0x20040080
	v_lshl_add_u64 v[144:145], v[142:143], 0, s[58:59]
	s_add_i32 s25, s6, 0x2000
	s_mov_b32 s37, m0
	s_mov_b32 m0, s25
	s_nop 0
	global_load_lds_dwordx4 v[144:145], off
	s_mov_b32 m0, s37
	s_mov_b64 s[58:59], 0x60000
	v_lshl_add_u64 v[140:141], v[140:141], 0, s[58:59]
	s_addk_i32 s7, 0x2000
	s_mov_b32 s25, m0
	s_mov_b32 m0, s7
	s_nop 0
	global_load_lds_dwordx4 v[140:141], off
	s_mov_b32 m0, s25
	s_mov_b64 s[58:59], 0x20060000
	v_lshl_add_u64 v[140:141], v[142:143], 0, s[58:59]
	s_add_i32 s7, s6, 0x4000
	s_mov_b32 s25, m0
	s_mov_b32 m0, s7
	s_nop 0
	global_load_lds_dwordx4 v[140:141], off
	s_mov_b32 m0, s25
	s_mov_b64 s[58:59], 0x20060080
	v_lshl_add_u64 v[140:141], v[142:143], 0, s[58:59]
	s_addk_i32 s6, 0x6000
	s_mov_b32 s7, m0
	s_mov_b32 m0, s6
	s_nop 0
	global_load_lds_dwordx4 v[140:141], off
	s_mov_b32 m0, s7
.LBB0_668:
	ds_read_b128 v[114:117], v226 offset:8192
	ds_read_b128 v[118:121], v226 offset:8704
	ds_read_b128 v[122:125], v226 offset:10240
	ds_read_b128 v[126:129], v226 offset:10752
	ds_read_b128 v[130:133], v226 offset:12288
	ds_read_b128 v[134:137], v226 offset:12800
	ds_read_b128 v[138:141], v226 offset:14336
	s_add_i32 s6, s73, s24
	s_waitcnt lgkmcnt(14)
	v_mfma_f32_32x32x16_bf16 v[146:161], v[82:85], v[210:213], v[66:81]
	ds_read_b128 v[142:145], v226 offset:14848
	s_waitcnt lgkmcnt(14)
	v_mfma_f32_32x32x16_bf16 v[162:177], v[86:89], v[210:213], v[66:81]
	s_waitcnt lgkmcnt(13)
	v_mfma_f32_32x32x16_bf16 v[146:161], v[90:93], v[214:217], v[146:161]
	s_waitcnt lgkmcnt(12)
	v_mfma_f32_32x32x16_bf16 v[162:177], v[94:97], v[214:217], v[162:177]
	s_waitcnt lgkmcnt(11)
	v_mfma_f32_32x32x16_bf16 v[146:161], v[98:101], v[218:221], v[146:161]
	s_waitcnt lgkmcnt(10)
	v_mfma_f32_32x32x16_bf16 v[162:177], v[102:105], v[218:221], v[162:177]
	s_waitcnt lgkmcnt(9)
	v_mfma_f32_32x32x16_bf16 v[146:161], v[106:109], v[222:225], v[146:161]
	s_waitcnt lgkmcnt(8)
	v_mfma_f32_32x32x16_bf16 v[162:177], v[110:113], v[222:225], v[162:177]
	s_waitcnt lgkmcnt(7)
	v_mfma_f32_32x32x16_bf16 v[178:193], v[114:117], v[210:213], v[66:81]
	s_waitcnt lgkmcnt(6)
	v_mfma_f32_32x32x16_bf16 v[194:209], v[118:121], v[210:213], v[66:81]
	s_waitcnt lgkmcnt(5)
	v_mfma_f32_32x32x16_bf16 v[178:193], v[122:125], v[214:217], v[178:193]
	s_waitcnt lgkmcnt(4)
	v_mfma_f32_32x32x16_bf16 v[194:209], v[126:129], v[214:217], v[194:209]
	s_waitcnt lgkmcnt(3)
	v_mfma_f32_32x32x16_bf16 v[178:193], v[130:133], v[218:221], v[178:193]
	s_waitcnt lgkmcnt(2)
	v_mfma_f32_32x32x16_bf16 v[194:209], v[134:137], v[218:221], v[194:209]
	s_waitcnt lgkmcnt(1)
	v_mfma_f32_32x32x16_bf16 v[178:193], v[138:141], v[222:225], v[178:193]
	s_waitcnt lgkmcnt(0)
	v_mfma_f32_32x32x16_bf16 v[194:209], v[142:145], v[222:225], v[194:209]
	s_cmp_lt_i32 s6, -2
	s_cbranch_scc1 .LBB0_670
	v_add_u32_e32 v82, s68, v234
	v_add_u32_e32 v83, 32, v82
	v_cmp_le_i32_e32 vcc, v83, v232
	v_add_u32_e32 v83, 33, v82
	v_add_u32_e32 v84, 0x60, v82
	v_cndmask_b32_e32 v162, v247, v162, vcc
	v_cmp_lt_i32_e32 vcc, v82, v232
	s_nop 1
	v_cndmask_b32_e32 v147, v247, v147, vcc
	v_cmp_le_i32_e32 vcc, v82, v232
	s_nop 1
	v_cndmask_b32_e32 v146, v247, v146, vcc
	v_cmp_le_i32_e32 vcc, v83, v232
	v_add_u32_e32 v83, 2, v82
	s_nop 0
	v_cndmask_b32_e32 v163, v247, v163, vcc
	v_cmp_le_i32_e32 vcc, v83, v232
	v_add_u32_e32 v83, 34, v82
	s_nop 0
	v_cndmask_b32_e32 v148, v247, v148, vcc
	v_cmp_le_i32_e32 vcc, v83, v232
	v_add_u32_e32 v83, 3, v82
	s_nop 0
	v_cndmask_b32_e32 v164, v247, v164, vcc
	v_cmp_le_i32_e32 vcc, v83, v232
	v_add_u32_e32 v83, 35, v82
	s_nop 0
	v_cndmask_b32_e32 v149, v247, v149, vcc
	v_cmp_le_i32_e32 vcc, v83, v232
	v_add_u32_e32 v83, 8, v82
	s_nop 0
	v_cndmask_b32_e32 v165, v247, v165, vcc
	v_cmp_le_i32_e32 vcc, v83, v232
	v_add_u32_e32 v83, 40, v82
	s_nop 0
	v_cndmask_b32_e32 v150, v247, v150, vcc
	v_cmp_le_i32_e32 vcc, v83, v232
	v_add_u32_e32 v83, 9, v82
	s_nop 0
	v_cndmask_b32_e32 v166, v247, v166, vcc
	v_cmp_le_i32_e32 vcc, v83, v232
	v_add_u32_e32 v83, 41, v82
	s_nop 0
	v_cndmask_b32_e32 v151, v247, v151, vcc
	v_cmp_le_i32_e32 vcc, v83, v232
	v_add_u32_e32 v83, 10, v82
	s_nop 0
	v_cndmask_b32_e32 v167, v247, v167, vcc
	v_cmp_le_i32_e32 vcc, v83, v232
	v_add_u32_e32 v83, 42, v82
	s_nop 0
	v_cndmask_b32_e32 v152, v247, v152, vcc
	v_cmp_le_i32_e32 vcc, v83, v232
	v_add_u32_e32 v83, 11, v82
	s_nop 0
	v_cndmask_b32_e32 v168, v247, v168, vcc
	v_cmp_le_i32_e32 vcc, v83, v232
	v_add_u32_e32 v83, 43, v82
	s_nop 0
	v_cndmask_b32_e32 v153, v247, v153, vcc
	v_cmp_le_i32_e32 vcc, v83, v232
	v_add_u32_e32 v83, 16, v82
	s_nop 0
	v_cndmask_b32_e32 v169, v247, v169, vcc
	v_cmp_le_i32_e32 vcc, v83, v232
	v_add_u32_e32 v83, 48, v82
	s_nop 0
	v_cndmask_b32_e32 v154, v247, v154, vcc
	v_cmp_le_i32_e32 vcc, v83, v232
	v_add_u32_e32 v83, 17, v82
	s_nop 0
	v_cndmask_b32_e32 v170, v247, v170, vcc
	v_cmp_le_i32_e32 vcc, v83, v232
	v_add_u32_e32 v83, 49, v82
	s_nop 0
	v_cndmask_b32_e32 v155, v247, v155, vcc
	v_cmp_le_i32_e32 vcc, v83, v232
	v_add_u32_e32 v83, 18, v82
	s_nop 0
	v_cndmask_b32_e32 v171, v247, v171, vcc
	v_cmp_le_i32_e32 vcc, v83, v232
	v_add_u32_e32 v83, 50, v82
	s_nop 0
	v_cndmask_b32_e32 v156, v247, v156, vcc
	v_cmp_le_i32_e32 vcc, v83, v232
	v_add_u32_e32 v83, 19, v82
	s_nop 0
	v_cndmask_b32_e32 v172, v247, v172, vcc
	v_cmp_le_i32_e32 vcc, v83, v232
	v_add_u32_e32 v83, 51, v82
	s_nop 0
	v_cndmask_b32_e32 v157, v247, v157, vcc
	v_cmp_le_i32_e32 vcc, v83, v232
	v_add_u32_e32 v83, 24, v82
	s_nop 0
	v_cndmask_b32_e32 v173, v247, v173, vcc
	v_cmp_le_i32_e32 vcc, v83, v232
	v_add_u32_e32 v83, 56, v82
	s_nop 0
	v_cndmask_b32_e32 v158, v247, v158, vcc
	v_cmp_le_i32_e32 vcc, v83, v232
	v_add_u32_e32 v83, 25, v82
	s_nop 0
	v_cndmask_b32_e32 v174, v247, v174, vcc
	v_cmp_le_i32_e32 vcc, v83, v232
	v_add_u32_e32 v83, 57, v82
	s_nop 0
	v_cndmask_b32_e32 v159, v247, v159, vcc
	v_cmp_le_i32_e32 vcc, v83, v232
	v_add_u32_e32 v83, 26, v82
	s_nop 0
	v_cndmask_b32_e32 v175, v247, v175, vcc
	v_cmp_le_i32_e32 vcc, v83, v232
	v_add_u32_e32 v83, 58, v82
	s_nop 0
	v_cndmask_b32_e32 v160, v247, v160, vcc
	v_cmp_le_i32_e32 vcc, v83, v232
	v_add_u32_e32 v83, 27, v82
	s_nop 0
	v_cndmask_b32_e32 v176, v247, v176, vcc
	v_cmp_le_i32_e32 vcc, v83, v232
	v_add_u32_e32 v83, 59, v82
	s_nop 0
	v_cndmask_b32_e32 v161, v247, v161, vcc
	v_cmp_le_i32_e32 vcc, v83, v232
	v_add_u32_e32 v83, 64, v82
	s_nop 0
	v_cndmask_b32_e32 v177, v247, v177, vcc
	v_cmp_le_i32_e32 vcc, v84, v232
	s_nop 1
	v_cndmask_b32_e32 v194, v247, v194, vcc
	v_cmp_lt_i32_e32 vcc, v83, v232
	s_nop 1
	v_cndmask_b32_e32 v179, v247, v179, vcc
	v_cmp_le_i32_e32 vcc, v83, v232
	v_add_u32_e32 v83, 0x61, v82
	s_nop 0
	v_cndmask_b32_e32 v178, v247, v178, vcc
	v_cmp_le_i32_e32 vcc, v83, v232
	v_add_u32_e32 v83, 0x42, v82
	s_nop 0
	v_cndmask_b32_e32 v195, v247, v195, vcc
	v_cmp_le_i32_e32 vcc, v83, v232
	v_add_u32_e32 v83, 0x62, v82
	s_nop 0
	v_cndmask_b32_e32 v180, v247, v180, vcc
	v_cmp_le_i32_e32 vcc, v83, v232
	v_add_u32_e32 v83, 0x43, v82
	s_nop 0
	v_cndmask_b32_e32 v196, v247, v196, vcc
	v_cmp_le_i32_e32 vcc, v83, v232
	v_add_u32_e32 v83, 0x63, v82
	s_nop 0
	v_cndmask_b32_e32 v181, v247, v181, vcc
	v_cmp_le_i32_e32 vcc, v83, v232
	v_add_u32_e32 v83, 0x48, v82
	s_nop 0
	v_cndmask_b32_e32 v197, v247, v197, vcc
	v_cmp_le_i32_e32 vcc, v83, v232
	v_add_u32_e32 v83, 0x68, v82
	s_nop 0
	v_cndmask_b32_e32 v182, v247, v182, vcc
	v_cmp_le_i32_e32 vcc, v83, v232
	v_add_u32_e32 v83, 0x49, v82
	s_nop 0
	v_cndmask_b32_e32 v198, v247, v198, vcc
	v_cmp_le_i32_e32 vcc, v83, v232
	v_add_u32_e32 v83, 0x69, v82
	s_nop 0
	v_cndmask_b32_e32 v183, v247, v183, vcc
	v_cmp_le_i32_e32 vcc, v83, v232
	v_add_u32_e32 v83, 0x4a, v82
	s_nop 0
	v_cndmask_b32_e32 v199, v247, v199, vcc
	v_cmp_le_i32_e32 vcc, v83, v232
	v_add_u32_e32 v83, 0x6a, v82
	s_nop 0
	v_cndmask_b32_e32 v184, v247, v184, vcc
	v_cmp_le_i32_e32 vcc, v83, v232
	v_add_u32_e32 v83, 0x4b, v82
	s_nop 0
	v_cndmask_b32_e32 v200, v247, v200, vcc
	v_cmp_le_i32_e32 vcc, v83, v232
	v_add_u32_e32 v83, 0x6b, v82
	s_nop 0
	v_cndmask_b32_e32 v185, v247, v185, vcc
	v_cmp_le_i32_e32 vcc, v83, v232
	v_add_u32_e32 v83, 0x50, v82
	s_nop 0
	v_cndmask_b32_e32 v201, v247, v201, vcc
	v_cmp_le_i32_e32 vcc, v83, v232
	v_add_u32_e32 v83, 0x70, v82
	s_nop 0
	v_cndmask_b32_e32 v186, v247, v186, vcc
	v_cmp_le_i32_e32 vcc, v83, v232
	v_add_u32_e32 v83, 0x51, v82
	s_nop 0
	v_cndmask_b32_e32 v202, v247, v202, vcc
	v_cmp_le_i32_e32 vcc, v83, v232
	v_add_u32_e32 v83, 0x71, v82
	s_nop 0
	v_cndmask_b32_e32 v187, v247, v187, vcc
	v_cmp_le_i32_e32 vcc, v83, v232
	v_add_u32_e32 v83, 0x52, v82
	s_nop 0
	v_cndmask_b32_e32 v203, v247, v203, vcc
	v_cmp_le_i32_e32 vcc, v83, v232
	v_add_u32_e32 v83, 0x72, v82
	s_nop 0
	v_cndmask_b32_e32 v188, v247, v188, vcc
	v_cmp_le_i32_e32 vcc, v83, v232
	v_add_u32_e32 v83, 0x53, v82
	s_nop 0
	v_cndmask_b32_e32 v204, v247, v204, vcc
	v_cmp_le_i32_e32 vcc, v83, v232
	v_add_u32_e32 v83, 0x73, v82
	s_nop 0
	v_cndmask_b32_e32 v189, v247, v189, vcc
	v_cmp_le_i32_e32 vcc, v83, v232
	v_add_u32_e32 v83, 0x58, v82
	s_nop 0
	v_cndmask_b32_e32 v205, v247, v205, vcc
	v_cmp_le_i32_e32 vcc, v83, v232
	v_add_u32_e32 v83, 0x78, v82
	s_nop 0
	v_cndmask_b32_e32 v190, v247, v190, vcc
	v_cmp_le_i32_e32 vcc, v83, v232
	v_add_u32_e32 v83, 0x59, v82
	s_nop 0
	v_cndmask_b32_e32 v206, v247, v206, vcc
	v_cmp_le_i32_e32 vcc, v83, v232
	v_add_u32_e32 v83, 0x79, v82
	s_nop 0
	v_cndmask_b32_e32 v191, v247, v191, vcc
	v_cmp_le_i32_e32 vcc, v83, v232
	v_add_u32_e32 v83, 0x5a, v82
	s_nop 0
	v_cndmask_b32_e32 v207, v247, v207, vcc
	v_cmp_le_i32_e32 vcc, v83, v232
	v_add_u32_e32 v83, 0x7a, v82
	s_nop 0
	v_cndmask_b32_e32 v192, v247, v192, vcc
	v_cmp_le_i32_e32 vcc, v83, v232
	v_add_u32_e32 v83, 0x5b, v82
	v_add_u32_e32 v82, 0x7b, v82
	v_cndmask_b32_e32 v208, v247, v208, vcc
	v_cmp_le_i32_e32 vcc, v83, v232
	s_nop 1
	v_cndmask_b32_e32 v193, v247, v193, vcc
	v_cmp_le_i32_e32 vcc, v82, v232
	s_nop 1
	v_cndmask_b32_e32 v209, v247, v209, vcc
.LBB0_670:
	v_max_f32_e32 v82, v147, v147
	v_max_f32_e32 v83, v146, v146
	v_max_f32_e32 v82, v83, v82
	v_max3_f32 v83, v148, v149, v163
	v_max3_f32 v82, v82, v162, v164
	v_max3_f32 v82, v82, v165, v150
	v_max3_f32 v83, v83, v152, v153
	v_max3_f32 v82, v82, v151, v166
	v_max3_f32 v83, v83, v168, v169
	v_max3_f32 v82, v82, v167, v154
	v_max3_f32 v83, v83, v156, v157
	v_max3_f32 v82, v82, v155, v170
	v_max3_f32 v83, v83, v172, v173
	v_max3_f32 v82, v82, v171, v158
	v_max3_f32 v83, v83, v160, v161
	v_max3_f32 v82, v82, v159, v174
	v_max3_f32 v83, v83, v176, v177
	v_max3_f32 v82, v82, v175, v83
	v_max_f32_e32 v84, v179, v179
	v_max_f32_e32 v85, v178, v178
	v_max_f32_e32 v84, v85, v84
	v_max3_f32 v85, v180, v181, v195
	v_max3_f32 v84, v84, v194, v196
	v_max3_f32 v84, v84, v197, v182
	v_max3_f32 v85, v85, v184, v185
	v_max3_f32 v84, v84, v183, v198
	v_max3_f32 v85, v85, v200, v201
	v_max3_f32 v84, v84, v199, v186
	v_max3_f32 v85, v85, v188, v189
	v_max3_f32 v84, v84, v187, v202
	v_max3_f32 v85, v85, v204, v205
	v_max3_f32 v84, v84, v203, v190
	v_max3_f32 v85, v85, v192, v193
	v_max3_f32 v84, v84, v191, v206
	v_max3_f32 v85, v85, v208, v209
	v_max3_f32 v84, v84, v207, v85
	v_mov_b32_e32 v83, v82
	v_mov_b32_e32 v85, v84
	s_nop 1
	v_permlane32_swap_b32_e32 v84, v85
	v_permlane32_swap_b32_e32 v82, v83
	v_max_f32_e32 v85, v85, v85
	v_max_f32_e32 v84, v84, v84
	v_max_f32_e32 v84, v84, v85
	s_cmp_lg_u32 s68, 0
	v_max3_f32 v226, v82, v83, v84
	s_cbranch_scc0 .LBB0_681
	s_mov_b32 s6, 0x41000000
	v_cmp_lt_f32_e32 vcc, s6, v226
	s_mov_b64 s[58:59], 0
	v_mov_b32_e32 v236, v235
	v_mov_b32_e32 v237, v0
	s_mov_b64 s[60:61], 0
	s_cbranch_vccz .LBB0_675
	v_max_f32_e32 v66, v226, v226
	v_max_f32_e32 v67, 0, v66
	v_exp_f32_e64 v66, -v67
	s_and_saveexec_b64 s[60:61], s[38:39]
	ds_write_b32 v231, v66
	s_or_b64 exec, exec, s[60:61]
	v_add_f32_e32 v236, v235, v67
	v_xor_b32_e32 v81, 0x80000000, v236
	v_sub_f32_e32 v161, v161, v67
	v_sub_f32_e32 v160, v160, v67
	v_sub_f32_e32 v159, v159, v67
	v_sub_f32_e32 v158, v158, v67
	v_sub_f32_e32 v157, v157, v67
	v_sub_f32_e32 v156, v156, v67
	v_sub_f32_e32 v155, v155, v67
	v_sub_f32_e32 v154, v154, v67
	v_sub_f32_e32 v153, v153, v67
	v_sub_f32_e32 v152, v152, v67
	v_sub_f32_e32 v151, v151, v67
	v_sub_f32_e32 v150, v150, v67
	v_sub_f32_e32 v149, v149, v67
	v_sub_f32_e32 v148, v148, v67
	v_sub_f32_e32 v147, v147, v67
	v_sub_f32_e32 v146, v146, v67
	v_sub_f32_e32 v177, v177, v67
	v_sub_f32_e32 v176, v176, v67
	v_sub_f32_e32 v175, v175, v67
	v_sub_f32_e32 v174, v174, v67
	v_sub_f32_e32 v173, v173, v67
	v_sub_f32_e32 v172, v172, v67
	v_sub_f32_e32 v171, v171, v67
	v_sub_f32_e32 v170, v170, v67
	v_sub_f32_e32 v169, v169, v67
	v_sub_f32_e32 v168, v168, v67
	v_sub_f32_e32 v167, v167, v67
	v_sub_f32_e32 v166, v166, v67
	v_sub_f32_e32 v165, v165, v67
	v_sub_f32_e32 v164, v164, v67
	v_sub_f32_e32 v163, v163, v67
	v_sub_f32_e32 v162, v162, v67
	v_sub_f32_e32 v193, v193, v67
	v_sub_f32_e32 v192, v192, v67
	v_sub_f32_e32 v191, v191, v67
	v_sub_f32_e32 v190, v190, v67
	v_sub_f32_e32 v189, v189, v67
	v_sub_f32_e32 v188, v188, v67
	v_sub_f32_e32 v187, v187, v67
	v_sub_f32_e32 v186, v186, v67
	v_sub_f32_e32 v185, v185, v67
	v_sub_f32_e32 v184, v184, v67
	v_sub_f32_e32 v183, v183, v67
	v_sub_f32_e32 v182, v182, v67
	v_sub_f32_e32 v181, v181, v67
	v_sub_f32_e32 v180, v180, v67
	v_sub_f32_e32 v179, v179, v67
	v_sub_f32_e32 v178, v178, v67
	v_sub_f32_e32 v209, v209, v67
	v_sub_f32_e32 v208, v208, v67
	v_sub_f32_e32 v207, v207, v67
	v_sub_f32_e32 v206, v206, v67
	v_sub_f32_e32 v205, v205, v67
	v_sub_f32_e32 v204, v204, v67
	v_sub_f32_e32 v203, v203, v67
	v_sub_f32_e32 v202, v202, v67
	v_sub_f32_e32 v201, v201, v67
	v_sub_f32_e32 v200, v200, v67
	v_sub_f32_e32 v199, v199, v67
	v_sub_f32_e32 v198, v198, v67
	v_sub_f32_e32 v197, v197, v67
	v_sub_f32_e32 v196, v196, v67
	v_sub_f32_e32 v195, v195, v67
	v_sub_f32_e32 v194, v194, v67
	v_mul_f32_e32 v237, v0, v66
	s_mov_b64 s[60:61], -1
	v_mov_b32_e32 v80, v81
	v_mov_b32_e32 v79, v81
	v_mov_b32_e32 v78, v81
	v_mov_b32_e32 v77, v81
	v_mov_b32_e32 v76, v81
	v_mov_b32_e32 v75, v81
	v_mov_b32_e32 v74, v81
	v_mov_b32_e32 v73, v81
	v_mov_b32_e32 v72, v81
	v_mov_b32_e32 v71, v81
	v_mov_b32_e32 v70, v81
	v_mov_b32_e32 v69, v81
	v_mov_b32_e32 v68, v81
	v_mov_b32_e32 v67, v81
	v_mov_b32_e32 v66, v81

.LBB0_676:
	v_add_f32_e32 v236, v235, v226
	v_xor_b32_e32 v66, 0x80000000, v236
	v_sub_f32_e32 v161, v161, v226
	v_sub_f32_e32 v160, v160, v226
	v_sub_f32_e32 v159, v159, v226
	v_sub_f32_e32 v158, v158, v226
	v_sub_f32_e32 v157, v157, v226
	v_sub_f32_e32 v156, v156, v226
	v_sub_f32_e32 v155, v155, v226
	v_sub_f32_e32 v154, v154, v226
	v_sub_f32_e32 v153, v153, v226
	v_sub_f32_e32 v152, v152, v226
	v_sub_f32_e32 v151, v151, v226
	v_sub_f32_e32 v150, v150, v226
	v_sub_f32_e32 v149, v149, v226
	v_sub_f32_e32 v148, v148, v226
	v_sub_f32_e32 v147, v147, v226
	v_sub_f32_e32 v146, v146, v226
	v_sub_f32_e32 v177, v177, v226
	v_sub_f32_e32 v176, v176, v226
	v_sub_f32_e32 v175, v175, v226
	v_sub_f32_e32 v174, v174, v226
	v_sub_f32_e32 v173, v173, v226
	v_sub_f32_e32 v172, v172, v226
	v_sub_f32_e32 v171, v171, v226
	v_sub_f32_e32 v170, v170, v226
	v_sub_f32_e32 v169, v169, v226
	v_sub_f32_e32 v168, v168, v226
	v_sub_f32_e32 v167, v167, v226
	v_sub_f32_e32 v166, v166, v226
	v_sub_f32_e32 v165, v165, v226
	v_sub_f32_e32 v164, v164, v226
	v_sub_f32_e32 v163, v163, v226
	v_sub_f32_e32 v162, v162, v226
	v_sub_f32_e32 v193, v193, v226
	v_sub_f32_e32 v192, v192, v226
	v_sub_f32_e32 v191, v191, v226
	v_sub_f32_e32 v190, v190, v226
	v_sub_f32_e32 v189, v189, v226
	v_sub_f32_e32 v188, v188, v226
	v_sub_f32_e32 v187, v187, v226
	v_sub_f32_e32 v186, v186, v226
	v_sub_f32_e32 v185, v185, v226
	v_sub_f32_e32 v184, v184, v226
	v_sub_f32_e32 v183, v183, v226
	v_sub_f32_e32 v182, v182, v226
	v_sub_f32_e32 v181, v181, v226
	v_sub_f32_e32 v180, v180, v226
	v_sub_f32_e32 v179, v179, v226
	v_sub_f32_e32 v178, v178, v226
	v_sub_f32_e32 v209, v209, v226
	v_sub_f32_e32 v208, v208, v226
	v_sub_f32_e32 v207, v207, v226
	v_sub_f32_e32 v206, v206, v226
	v_sub_f32_e32 v205, v205, v226
	v_sub_f32_e32 v204, v204, v226
	v_sub_f32_e32 v203, v203, v226
	v_sub_f32_e32 v202, v202, v226
	v_sub_f32_e32 v201, v201, v226
	v_sub_f32_e32 v200, v200, v226
	v_sub_f32_e32 v199, v199, v226
	v_sub_f32_e32 v198, v198, v226
	v_sub_f32_e32 v197, v197, v226
	v_sub_f32_e32 v196, v196, v226
	v_sub_f32_e32 v195, v195, v226
	v_sub_f32_e32 v194, v194, v226
	s_mov_b64 s[60:61], 0
	v_mov_b32_e32 v237, v0
	v_mov_b32_e32 v67, v66
	v_mov_b32_e32 v68, v66
	v_mov_b32_e32 v69, v66
	v_mov_b32_e32 v70, v66
	v_mov_b32_e32 v71, v66
	v_mov_b32_e32 v72, v66
	v_mov_b32_e32 v73, v66
	v_mov_b32_e32 v74, v66
	v_mov_b32_e32 v75, v66
	v_mov_b32_e32 v76, v66
	v_mov_b32_e32 v77, v66
	v_mov_b32_e32 v78, v66
	v_mov_b32_e32 v79, v66
	v_mov_b32_e32 v80, v66
	v_mov_b32_e32 v81, v66

.LBB0_679:
	v_exp_f32_e32 v226, v146
	v_exp_f32_e32 v162, v162
	v_exp_f32_e32 v144, v178
	v_exp_f32_e32 v142, v194
	v_exp_f32_e32 v227, v147
	v_exp_f32_e32 v163, v163
	v_exp_f32_e32 v146, v179
	v_exp_f32_e32 v143, v195
	v_exp_f32_e32 v235, v148
	v_exp_f32_e32 v164, v164
	v_exp_f32_e32 v148, v180
	v_exp_f32_e32 v145, v196
	v_exp_f32_e32 v228, v149
	v_exp_f32_e32 v165, v165
	v_exp_f32_e32 v229, v150
	v_exp_f32_e32 v150, v181
	v_exp_f32_e32 v147, v197
	v_add_f32_e32 v0, v162, v226
	v_exp_f32_e32 v166, v166
	v_exp_f32_e32 v99, v151
	v_add_f32_e32 v82, v144, v142
	v_exp_f32_e32 v151, v182
	v_exp_f32_e32 v149, v198
	v_add_f32_e32 v85, v163, v227
	v_exp_f32_e32 v113, v167
	v_add_f32_e32 v82, 0, v82
	v_add_f32_e32 v84, v146, v143
	v_exp_f32_e32 v112, v183
	v_exp_f32_e32 v98, v199
	v_add_f32_e32 v0, 0, v0
	v_add_f32_e32 v86, v164, v235
	v_exp_f32_e32 v101, v152
	v_exp_f32_e32 v117, v168
	v_add_f32_e32 v82, v84, v82
	v_add_f32_e32 v84, v148, v145
	v_exp_f32_e32 v116, v184
	v_exp_f32_e32 v100, v200
	v_add_f32_e32 v0, v85, v0
	v_add_f32_e32 v87, v165, v228
	v_exp_f32_e32 v103, v153
	v_exp_f32_e32 v121, v169
	v_add_f32_e32 v82, v84, v82
	v_add_f32_e32 v84, v150, v147
	v_exp_f32_e32 v120, v185
	v_exp_f32_e32 v102, v201
	v_add_f32_e32 v0, v86, v0
	v_add_f32_e32 v83, v166, v229
	v_exp_f32_e32 v105, v154
	v_exp_f32_e32 v125, v170
	v_add_f32_e32 v84, v84, v82
	v_add_f32_e32 v82, v151, v149
	v_exp_f32_e32 v124, v186
	v_exp_f32_e32 v104, v202
	v_add_f32_e32 v85, v87, v0
	v_exp_f32_e32 v107, v155
	v_exp_f32_e32 v129, v171
	v_exp_f32_e32 v128, v187
	v_exp_f32_e32 v106, v203
	v_pk_add_f32 v[86:87], v[112:113], v[98:99]
	v_pk_add_f32 v[82:83], v[82:83], v[84:85]
	v_exp_f32_e32 v109, v156
	v_exp_f32_e32 v131, v172
	v_exp_f32_e32 v130, v188
	v_exp_f32_e32 v108, v204
	v_pk_add_f32 v[88:89], v[116:117], v[100:101]
	v_pk_add_f32 v[82:83], v[86:87], v[82:83]
	v_exp_f32_e32 v111, v157
	v_exp_f32_e32 v133, v173
	v_exp_f32_e32 v132, v189
	v_exp_f32_e32 v110, v205
	v_pk_add_f32 v[90:91], v[120:121], v[102:103]
	v_pk_add_f32 v[82:83], v[88:89], v[82:83]
	v_exp_f32_e32 v115, v158
	v_exp_f32_e32 v135, v174
	v_exp_f32_e32 v134, v190
	v_exp_f32_e32 v114, v206
	v_pk_add_f32 v[92:93], v[124:125], v[104:105]
	v_pk_add_f32 v[82:83], v[90:91], v[82:83]
	v_exp_f32_e32 v119, v159
	v_exp_f32_e32 v137, v175
	v_exp_f32_e32 v136, v191
	v_exp_f32_e32 v118, v207
	v_pk_add_f32 v[94:95], v[128:129], v[106:107]
	v_pk_add_f32 v[82:83], v[92:93], v[82:83]
	v_exp_f32_e32 v123, v160
	v_exp_f32_e32 v139, v176
	v_exp_f32_e32 v138, v192
	v_exp_f32_e32 v122, v208
	v_pk_add_f32 v[96:97], v[130:131], v[108:109]
	v_pk_add_f32 v[82:83], v[94:95], v[82:83]
	v_exp_f32_e32 v127, v161
	v_exp_f32_e32 v141, v177
	v_exp_f32_e32 v140, v193
	v_exp_f32_e32 v126, v209
	v_pk_add_f32 v[152:153], v[132:133], v[110:111]
	v_pk_add_f32 v[82:83], v[96:97], v[82:83]
	v_cvt_pk_bf16_f32 v94, v226, v227
	v_cvt_pk_bf16_f32 v95, v235, v228
	v_cvt_pk_bf16_f32 v96, v229, v99
	v_cvt_pk_bf16_f32 v97, v101, v103
	v_pk_add_f32 v[154:155], v[134:135], v[114:115]
	v_pk_add_f32 v[82:83], v[152:153], v[82:83]
	v_pk_add_f32 v[156:157], v[136:137], v[118:119]
	v_pk_add_f32 v[82:83], v[154:155], v[82:83]
	v_pk_add_f32 v[158:159], v[138:139], v[122:123]
	v_pk_add_f32 v[82:83], v[156:157], v[82:83]
	v_pk_add_f32 v[160:161], v[140:141], v[126:127]
	v_pk_add_f32 v[82:83], v[158:159], v[82:83]
	v_lshl_add_u32 v99, s36, 15, v230
	v_pk_add_f32 v[82:83], v[160:161], v[82:83]
	v_cvt_pk_bf16_f32 v86, v162, v163
	v_cvt_pk_bf16_f32 v87, v164, v165
	v_cvt_pk_bf16_f32 v88, v166, v113
	ds_read_b64_tr_b16 v[152:153], v99 offset:32768
	ds_read_b64_tr_b16 v[154:155], v99 offset:33280
	ds_read_b64_tr_b16 v[156:157], v99 offset:33792
	ds_read_b64_tr_b16 v[158:159], v99 offset:34304
	ds_read_b64_tr_b16 v[160:161], v99 offset:34816
	ds_read_b64_tr_b16 v[162:163], v99 offset:35328
	ds_read_b64_tr_b16 v[164:165], v99 offset:35840
	ds_read_b64_tr_b16 v[166:167], v99 offset:36352
	ds_read_b64_tr_b16 v[168:169], v99 offset:36864
	ds_read_b64_tr_b16 v[170:171], v99 offset:37376
	ds_read_b64_tr_b16 v[172:173], v99 offset:37888
	ds_read_b64_tr_b16 v[174:175], v99 offset:38400
	s_waitcnt lgkmcnt(10)
	v_mfma_f32_32x32x16_bf16 v[50:65], v[94:97], v[152:155], v[50:65]
	ds_read_b64_tr_b16 v[176:177], v99 offset:38912
	ds_read_b64_tr_b16 v[178:179], v99 offset:39424
	v_cvt_pk_bf16_f32 v90, v105, v107
	v_cvt_pk_bf16_f32 v91, v109, v111
	v_cvt_pk_bf16_f32 v92, v115, v119
	v_cvt_pk_bf16_f32 v93, v123, v127
	v_cvt_pk_bf16_f32 v89, v117, v121
	v_add_f32_e32 v0, v82, v83
	v_cvt_pk_bf16_f32 v82, v125, v129
	s_waitcnt lgkmcnt(10)
	v_mfma_f32_32x32x16_bf16 v[50:65], v[90:93], v[156:159], v[50:65]
	ds_read_b64_tr_b16 v[180:181], v99 offset:39936
	ds_read_b64_tr_b16 v[182:183], v99 offset:40448
	v_cvt_pk_bf16_f32 v83, v131, v133
	v_cvt_pk_bf16_f32 v84, v135, v137
	v_cvt_pk_bf16_f32 v85, v139, v141
	s_addk_i32 s68, 0x80
	s_add_u32 s56, s56, 0x40000
	s_addc_u32 s57, s57, 0
	v_add_f32_e32 v0, v237, v0
	s_waitcnt lgkmcnt(10)
	v_mfma_f32_32x32x16_bf16 v[50:65], v[86:89], v[160:163], v[50:65]
	ds_read_b64_tr_b16 v[152:153], v99 offset:40960
	ds_read_b64_tr_b16 v[154:155], v99 offset:41472
	s_cmp_eq_u32 s74, s56
	s_waitcnt lgkmcnt(10)
	v_mfma_f32_32x32x16_bf16 v[50:65], v[82:85], v[164:167], v[50:65]
	ds_read_b64_tr_b16 v[156:157], v99 offset:41984
	ds_read_b64_tr_b16 v[158:159], v99 offset:42496
	s_waitcnt lgkmcnt(10)
	v_mfma_f32_32x32x16_bf16 v[34:49], v[94:97], v[168:171], v[34:49]
	ds_read_b64_tr_b16 v[160:161], v99 offset:43008
	ds_read_b64_tr_b16 v[162:163], v99 offset:43520
	s_waitcnt lgkmcnt(10)
	v_mfma_f32_32x32x16_bf16 v[34:49], v[90:93], v[172:175], v[34:49]
	ds_read_b64_tr_b16 v[164:165], v99 offset:44032
	ds_read_b64_tr_b16 v[166:167], v99 offset:44544
	s_waitcnt lgkmcnt(10)
	v_mfma_f32_32x32x16_bf16 v[34:49], v[86:89], v[176:179], v[34:49]
	ds_read_b64_tr_b16 v[168:169], v99 offset:45056
	ds_read_b64_tr_b16 v[170:171], v99 offset:45568
	s_waitcnt lgkmcnt(10)
	v_mfma_f32_32x32x16_bf16 v[34:49], v[82:85], v[180:183], v[34:49]
	ds_read_b64_tr_b16 v[172:173], v99 offset:46080
	ds_read_b64_tr_b16 v[174:175], v99 offset:46592
	s_waitcnt lgkmcnt(10)
	v_mfma_f32_32x32x16_bf16 v[18:33], v[94:97], v[152:155], v[18:33]
	ds_read_b64_tr_b16 v[176:177], v99 offset:47104
	ds_read_b64_tr_b16 v[178:179], v99 offset:47616
	s_waitcnt lgkmcnt(10)
	v_mfma_f32_32x32x16_bf16 v[18:33], v[90:93], v[156:159], v[18:33]
	ds_read_b64_tr_b16 v[180:181], v99 offset:48128
	ds_read_b64_tr_b16 v[182:183], v99 offset:48640
	s_waitcnt lgkmcnt(10)
	v_mfma_f32_32x32x16_bf16 v[18:33], v[86:89], v[160:163], v[18:33]
	ds_read_b64_tr_b16 v[152:153], v99 offset:49152
	ds_read_b64_tr_b16 v[154:155], v99 offset:49664
	s_waitcnt lgkmcnt(10)
	v_mfma_f32_32x32x16_bf16 v[18:33], v[82:85], v[164:167], v[18:33]
	ds_read_b64_tr_b16 v[156:157], v99 offset:50176
	ds_read_b64_tr_b16 v[158:159], v99 offset:50688
	s_waitcnt lgkmcnt(10)
	v_mfma_f32_32x32x16_bf16 v[2:17], v[94:97], v[168:171], v[2:17]
	ds_read_b64_tr_b16 v[160:161], v99 offset:51200
	ds_read_b64_tr_b16 v[162:163], v99 offset:51712
	v_cvt_pk_bf16_f32 v94, v144, v146
	v_cvt_pk_bf16_f32 v95, v148, v150
	v_cvt_pk_bf16_f32 v96, v151, v112
	v_cvt_pk_bf16_f32 v97, v116, v120
	s_waitcnt lgkmcnt(10)
	v_mfma_f32_32x32x16_bf16 v[2:17], v[90:93], v[172:175], v[2:17]
	ds_read_b64_tr_b16 v[164:165], v99 offset:52224
	ds_read_b64_tr_b16 v[166:167], v99 offset:52736
	v_cvt_pk_bf16_f32 v90, v124, v128
	v_cvt_pk_bf16_f32 v91, v130, v132
	v_cvt_pk_bf16_f32 v92, v134, v136
	v_cvt_pk_bf16_f32 v93, v138, v140
	s_waitcnt lgkmcnt(10)
	v_mfma_f32_32x32x16_bf16 v[2:17], v[86:89], v[176:179], v[2:17]
	ds_read_b64_tr_b16 v[168:169], v99 offset:53248
	ds_read_b64_tr_b16 v[170:171], v99 offset:53760
	v_cvt_pk_bf16_f32 v86, v104, v106
	v_cvt_pk_bf16_f32 v87, v108, v110
	v_cvt_pk_bf16_f32 v88, v114, v118
	v_cvt_pk_bf16_f32 v89, v122, v126
	s_waitcnt lgkmcnt(10)
	v_mfma_f32_32x32x16_bf16 v[2:17], v[82:85], v[180:183], v[2:17]
	ds_read_b64_tr_b16 v[172:173], v99 offset:54272
	ds_read_b64_tr_b16 v[174:175], v99 offset:54784
	v_cvt_pk_bf16_f32 v85, v100, v102
	v_cvt_pk_bf16_f32 v82, v142, v143
	v_cvt_pk_bf16_f32 v83, v145, v147
	v_cvt_pk_bf16_f32 v84, v149, v98
	s_waitcnt lgkmcnt(10)
	v_mfma_f32_32x32x16_bf16 v[50:65], v[94:97], v[152:155], v[50:65]
	ds_read_b64_tr_b16 v[176:177], v99 offset:55296
	ds_read_b64_tr_b16 v[178:179], v99 offset:55808
	s_waitcnt lgkmcnt(10)
	v_mfma_f32_32x32x16_bf16 v[50:65], v[90:93], v[156:159], v[50:65]
	ds_read_b64_tr_b16 v[180:181], v99 offset:56320
	ds_read_b64_tr_b16 v[182:183], v99 offset:56832
	s_waitcnt lgkmcnt(10)
	v_mfma_f32_32x32x16_bf16 v[50:65], v[82:85], v[160:163], v[50:65]
	ds_read_b64_tr_b16 v[152:153], v99 offset:57344
	ds_read_b64_tr_b16 v[154:155], v99 offset:57856
	s_waitcnt lgkmcnt(10)
	v_mfma_f32_32x32x16_bf16 v[50:65], v[86:89], v[164:167], v[50:65]
	ds_read_b64_tr_b16 v[156:157], v99 offset:58368
	ds_read_b64_tr_b16 v[158:159], v99 offset:58880
	s_waitcnt lgkmcnt(10)
	v_mfma_f32_32x32x16_bf16 v[34:49], v[94:97], v[168:171], v[34:49]
	ds_read_b64_tr_b16 v[160:161], v99 offset:59392
	ds_read_b64_tr_b16 v[162:163], v99 offset:59904
	s_waitcnt lgkmcnt(10)
	v_mfma_f32_32x32x16_bf16 v[34:49], v[90:93], v[172:175], v[34:49]
	ds_read_b64_tr_b16 v[164:165], v99 offset:60416
	ds_read_b64_tr_b16 v[166:167], v99 offset:60928
	s_waitcnt lgkmcnt(10)
	v_mfma_f32_32x32x16_bf16 v[34:49], v[82:85], v[176:179], v[34:49]
	ds_read_b64_tr_b16 v[168:169], v99 offset:61440
	ds_read_b64_tr_b16 v[170:171], v99 offset:61952
	s_waitcnt lgkmcnt(10)
	v_mfma_f32_32x32x16_bf16 v[34:49], v[86:89], v[180:183], v[34:49]
	ds_read_b64_tr_b16 v[172:173], v99 offset:62464
	ds_read_b64_tr_b16 v[174:175], v99 offset:62976
	s_waitcnt lgkmcnt(10)
	v_mfma_f32_32x32x16_bf16 v[18:33], v[94:97], v[152:155], v[18:33]
	ds_read_b64_tr_b16 v[176:177], v99 offset:63488
	ds_read_b64_tr_b16 v[178:179], v99 offset:64000
	s_waitcnt lgkmcnt(10)
	v_mfma_f32_32x32x16_bf16 v[18:33], v[90:93], v[156:159], v[18:33]
	ds_read_b64_tr_b16 v[180:181], v99 offset:64512
	ds_read_b64_tr_b16 v[182:183], v99 offset:65024
	s_waitcnt lgkmcnt(10)
	v_mfma_f32_32x32x16_bf16 v[18:33], v[82:85], v[160:163], v[18:33]
	s_waitcnt lgkmcnt(8)
	v_mfma_f32_32x32x16_bf16 v[18:33], v[86:89], v[164:167], v[18:33]
	s_waitcnt lgkmcnt(6)
	v_mfma_f32_32x32x16_bf16 v[2:17], v[94:97], v[168:171], v[2:17]
	s_waitcnt lgkmcnt(4)
	v_mfma_f32_32x32x16_bf16 v[2:17], v[90:93], v[172:175], v[2:17]
	s_waitcnt lgkmcnt(2)
	v_mfma_f32_32x32x16_bf16 v[2:17], v[82:85], v[176:179], v[2:17]
	s_waitcnt lgkmcnt(0)
	v_mfma_f32_32x32x16_bf16 v[2:17], v[86:89], v[180:183], v[2:17]
	s_cbranch_scc1 .LBB0_682
	v_mov_b32_e32 v235, v236
	s_mov_b32 s24, s75
	s_branch .LBB0_666
